# GLA scan rewritten by hand: 4 state columns per thread (16-byte loads, 8-byte stores, 3 waves per WG), batches of 8 steps with next batch loads issued ahead; same f32 fma arithmetic
# speedup vs baseline: 1.0150x; 1.0024x over previous
.LBB0_344:
	v_writelane_b32 v255, s95, 52
	s_or_b64 exec, exec, s[4:5]
	s_mov_b64 s[4:5], s[70:71]
	v_mov_b32_e32 v2, v0
	s_waitcnt lgkmcnt(0)
	s_barrier
	v_readlane_b32 s6, v255, 53
	v_add_u32_e32 v3, s40, v2
	s_lshl_b32 s88, s6, 9
	v_cmp_gt_u32_e32 vcc, 0xc0, v2
	s_mov_b64 s[6:7], exec
	v_writelane_b32 v255, s6, 58
	s_and_b64 s[8:9], s[6:7], vcc
	s_mov_b32 vcc_lo, 0x2aaaaaab
	v_writelane_b32 v255, s7, 59
	s_movk_i32 vcc_hi, 0xfd00
	s_mov_b32 s46, 0xc0000
	s_mov_b32 s54, 0xf0000
	s_mov_b32 s55, 0x120000
	s_mov_b32 s56, 0x150000
	s_mov_b32 s58, 0x180000
	s_mov_b32 s59, 0x1b0000
	s_mov_b32 s60, 0x1e0000
	s_mov_b32 s63, 0x210000
	s_mov_b32 s66, 0x240000
	s_mov_b32 s67, 0x270000
	s_mov_b32 s68, 0x2a0000
	s_mov_b32 s76, 0x2d0000
	s_mov_b32 s81, 0x300000
	s_mov_b32 s89, 0x330000
	s_mov_b32 s94, 0x360000
	s_mov_b32 s90, 0x390000
	s_mov_b32 s35, 0x3c0000
	s_mov_b32 s86, 0x3f0000
	s_mov_b32 s87, 0x420000
	s_mov_b32 s38, 0x450000
	s_mov_b32 s80, 0x480000
	s_mov_b32 s72, 0x4e0000
	s_mov_b32 s84, 0x510000
	s_mov_b32 s85, 0x540000
	s_mov_b32 s95, 0x570000
	s_mov_b32 s6, 0x5a0000
	s_mov_b32 s7, 0x630000
	s_mov_b32 s39, 0x660000
	s_mov_b32 s16, 0x750000
	s_mov_b32 s17, 0x780000
	s_mov_b32 s18, 0x7b0000
	s_mov_b32 s19, 0x7e0000
	s_mov_b32 s20, 0x810000
	s_mov_b32 s21, 0x840000
	s_mov_b32 s22, 0x870000
	s_mov_b32 s23, 0x8a0000
	s_mov_b32 s24, 0x8d0000
	s_mov_b32 s25, 0x900000
	s_mov_b32 s26, 0x930000
	s_mov_b32 s27, 0x960000
	s_mov_b32 s28, 0x990000
	s_mov_b32 s29, 0x9c0000
	s_mov_b32 s30, 0x9f0000
	s_mov_b32 s33, 0xa20000
	s_mov_b32 s61, 0xa50000
	s_mov_b32 s40, 0xa80000
	s_mov_b32 s70, 0xab0000
	s_mov_b32 s71, 0xae0000
	s_mov_b32 s91, 0xb10000
	s_mov_b32 s73, 0xb40000
	s_mov_b32 s31, 0xb70000
	s_mov_b32 s34, 0xba0000
	s_mov_b32 s36, 0x4b0000
	s_mov_b32 s37, 0x5d0000
	s_mov_b64 exec, s[8:9]
	s_cbranch_execz .LBB0_347
	s_load_dwordx4 s[12:15], s[4:5], 0x80
	s_waitcnt lgkmcnt(0)
	s_add_u32 s8, s12, 0x8000000
	s_addc_u32 s9, s13, 0
	s_add_u32 s10, s14, 0x400000
	s_addc_u32 s11, s15, 0
	s_add_u32 s12, s14, 0x5b400000
	s_addc_u32 s13, s15, 0
	s_mov_b64 s[14:15], 0
.LBB0_346:
	v_lshrrev_b32_e32 v35, 9, v3
	v_mul_u32_u24_e32 v35, 0xc0, v35
	v_add_u32_e32 v3, v35, v2
	v_and_b32_e32 v35, 15, v3
	v_lshlrev_b32_e32 v35, 4, v35
	v_lshrrev_b32_e32 v36, 4, v3
	v_lshrrev_b32_e32 v37, 8, v36
	v_mul_u32_u24_e32 v37, 11, v37
	v_lshrrev_b32_e32 v37, 5, v37
	v_mul_u32_u24_e32 v38, 0x300, v37
	v_sub_u32_e32 v38, v36, v38
	v_lshrrev_b32_e32 v39, 7, v38
	v_mul_u32_u24_e32 v32, 3, v37
	v_lshlrev_b32_e32 v32, 23, v32
	v_lshl_add_u32 v32, v38, 8, v32
	v_add_u32_e32 v32, v32, v35
	v_lshrrev_b32_e32 v34, 1, v32
	v_mul_u32_u24_e32 v33, 0x30000, v37
	v_lshl_add_u32 v33, v39, 8, v33
	v_add_u32_e32 v33, v33, v35
	v_mov_b32_e32 v24, 0
	v_mov_b32_e32 v25, 0
	v_mov_b32_e32 v26, 0
	v_mov_b32_e32 v27, 0
	s_mov_b32 s4, 0x30000
	s_movk_i32 s5, 0x600
	s_mov_b32 s43, 0x18000
	global_load_dwordx4 v[130:133], v32, s[8:9]
	global_load_dwordx4 v[134:137], v33, s[10:11]
	v_add_u32_e32 v32, s4, v32
	v_add_u32_e32 v33, s5, v33
	global_load_dwordx4 v[138:141], v32, s[8:9]
	global_load_dwordx4 v[142:145], v33, s[10:11]
	v_add_u32_e32 v32, s4, v32
	v_add_u32_e32 v33, s5, v33
	global_load_dwordx4 v[146:149], v32, s[8:9]
	global_load_dwordx4 v[150:153], v33, s[10:11]
	v_add_u32_e32 v32, s4, v32
	v_add_u32_e32 v33, s5, v33
	global_load_dwordx4 v[154:157], v32, s[8:9]
	global_load_dwordx4 v[158:161], v33, s[10:11]
	v_add_u32_e32 v32, s4, v32
	v_add_u32_e32 v33, s5, v33
	global_load_dwordx4 v[162:165], v32, s[8:9]
	global_load_dwordx4 v[166:169], v33, s[10:11]
	v_add_u32_e32 v32, s4, v32
	v_add_u32_e32 v33, s5, v33
	global_load_dwordx4 v[170:173], v32, s[8:9]
	global_load_dwordx4 v[174:177], v33, s[10:11]
	v_add_u32_e32 v32, s4, v32
	v_add_u32_e32 v33, s5, v33
	global_load_dwordx4 v[178:181], v32, s[8:9]
	global_load_dwordx4 v[182:185], v33, s[10:11]
	v_add_u32_e32 v32, s4, v32
	v_add_u32_e32 v33, s5, v33
	global_load_dwordx4 v[186:189], v32, s[8:9]
	global_load_dwordx4 v[190:193], v33, s[10:11]
	v_add_u32_e32 v32, s4, v32
	v_add_u32_e32 v33, s5, v33
	global_load_dwordx4 v[194:197], v32, s[8:9]
	global_load_dwordx4 v[198:201], v33, s[10:11]
	v_add_u32_e32 v32, s4, v32
	v_add_u32_e32 v33, s5, v33
	global_load_dwordx4 v[202:205], v32, s[8:9]
	global_load_dwordx4 v[206:209], v33, s[10:11]
	v_add_u32_e32 v32, s4, v32
	v_add_u32_e32 v33, s5, v33
	global_load_dwordx4 v[212:215], v32, s[8:9]
	global_load_dwordx4 v[216:219], v33, s[10:11]
	v_add_u32_e32 v32, s4, v32
	v_add_u32_e32 v33, s5, v33
	global_load_dwordx4 v[220:223], v32, s[8:9]
	global_load_dwordx4 v[224:227], v33, s[10:11]
	v_add_u32_e32 v32, s4, v32
	v_add_u32_e32 v33, s5, v33
	global_load_dwordx4 v[228:231], v32, s[8:9]
	global_load_dwordx4 v[66:69], v33, s[10:11]
	v_add_u32_e32 v32, s4, v32
	v_add_u32_e32 v33, s5, v33
	global_load_dwordx4 v[70:73], v32, s[8:9]
	global_load_dwordx4 v[74:77], v33, s[10:11]
	v_add_u32_e32 v32, s4, v32
	v_add_u32_e32 v33, s5, v33
	global_load_dwordx4 v[78:81], v32, s[8:9]
	global_load_dwordx4 v[8:11], v33, s[10:11]
	v_add_u32_e32 v32, s4, v32
	v_add_u32_e32 v33, s5, v33
	global_load_dwordx4 v[12:15], v32, s[8:9]
	global_load_dwordx4 v[16:19], v33, s[10:11]
	v_add_u32_e32 v32, s4, v32
	v_add_u32_e32 v33, s5, v33
	s_waitcnt vmcnt(16)
	v_cvt_pk_bf16_f32 v28, v24, v25
	v_cvt_pk_bf16_f32 v29, v26, v27
	global_store_dwordx2 v34, v[28:29], s[12:13]
	v_add_u32_e32 v34, s43, v34
	v_fmac_f32_e32 v130, v24, v134
	v_fmac_f32_e32 v131, v25, v135
	v_fmac_f32_e32 v132, v26, v136
	v_fmac_f32_e32 v133, v27, v137
	v_cvt_pk_bf16_f32 v30, v130, v131
	v_cvt_pk_bf16_f32 v31, v132, v133
	global_store_dwordx2 v34, v[30:31], s[12:13]
	v_add_u32_e32 v34, s43, v34
	v_fmac_f32_e32 v138, v130, v142
	v_fmac_f32_e32 v139, v131, v143
	v_fmac_f32_e32 v140, v132, v144
	v_fmac_f32_e32 v141, v133, v145
	v_cvt_pk_bf16_f32 v28, v138, v139
	v_cvt_pk_bf16_f32 v29, v140, v141
	global_store_dwordx2 v34, v[28:29], s[12:13]
	v_add_u32_e32 v34, s43, v34
	v_fmac_f32_e32 v146, v138, v150
	v_fmac_f32_e32 v147, v139, v151
	v_fmac_f32_e32 v148, v140, v152
	v_fmac_f32_e32 v149, v141, v153
	v_cvt_pk_bf16_f32 v30, v146, v147
	v_cvt_pk_bf16_f32 v31, v148, v149
	global_store_dwordx2 v34, v[30:31], s[12:13]
	v_add_u32_e32 v34, s43, v34
	v_fmac_f32_e32 v154, v146, v158
	v_fmac_f32_e32 v155, v147, v159
	v_fmac_f32_e32 v156, v148, v160
	v_fmac_f32_e32 v157, v149, v161
	v_cvt_pk_bf16_f32 v28, v154, v155
	v_cvt_pk_bf16_f32 v29, v156, v157
	global_store_dwordx2 v34, v[28:29], s[12:13]
	v_add_u32_e32 v34, s43, v34
	v_fmac_f32_e32 v162, v154, v166
	v_fmac_f32_e32 v163, v155, v167
	v_fmac_f32_e32 v164, v156, v168
	v_fmac_f32_e32 v165, v157, v169
	v_cvt_pk_bf16_f32 v30, v162, v163
	v_cvt_pk_bf16_f32 v31, v164, v165
	global_store_dwordx2 v34, v[30:31], s[12:13]
	v_add_u32_e32 v34, s43, v34
	v_fmac_f32_e32 v170, v162, v174
	v_fmac_f32_e32 v171, v163, v175
	v_fmac_f32_e32 v172, v164, v176
	v_fmac_f32_e32 v173, v165, v177
	v_cvt_pk_bf16_f32 v28, v170, v171
	v_cvt_pk_bf16_f32 v29, v172, v173
	global_store_dwordx2 v34, v[28:29], s[12:13]
	v_add_u32_e32 v34, s43, v34
	v_fmac_f32_e32 v178, v170, v182
	v_fmac_f32_e32 v179, v171, v183
	v_fmac_f32_e32 v180, v172, v184
	v_fmac_f32_e32 v181, v173, v185
	v_cvt_pk_bf16_f32 v30, v178, v179
	v_cvt_pk_bf16_f32 v31, v180, v181
	global_store_dwordx2 v34, v[30:31], s[12:13]
	v_add_u32_e32 v34, s43, v34
	v_fmac_f32_e32 v186, v178, v190
	v_fmac_f32_e32 v187, v179, v191
	v_fmac_f32_e32 v188, v180, v192
	v_fmac_f32_e32 v189, v181, v193
	v_mov_b32_e32 v24, v186
	v_mov_b32_e32 v25, v187
	v_mov_b32_e32 v26, v188
	v_mov_b32_e32 v27, v189
	global_load_dwordx4 v[130:133], v32, s[8:9]
	global_load_dwordx4 v[134:137], v33, s[10:11]
	v_add_u32_e32 v32, s4, v32
	v_add_u32_e32 v33, s5, v33
	global_load_dwordx4 v[138:141], v32, s[8:9]
	global_load_dwordx4 v[142:145], v33, s[10:11]
	v_add_u32_e32 v32, s4, v32
	v_add_u32_e32 v33, s5, v33
	global_load_dwordx4 v[146:149], v32, s[8:9]
	global_load_dwordx4 v[150:153], v33, s[10:11]
	v_add_u32_e32 v32, s4, v32
	v_add_u32_e32 v33, s5, v33
	global_load_dwordx4 v[154:157], v32, s[8:9]
	global_load_dwordx4 v[158:161], v33, s[10:11]
	v_add_u32_e32 v32, s4, v32
	v_add_u32_e32 v33, s5, v33
	global_load_dwordx4 v[162:165], v32, s[8:9]
	global_load_dwordx4 v[166:169], v33, s[10:11]
	v_add_u32_e32 v32, s4, v32
	v_add_u32_e32 v33, s5, v33
	global_load_dwordx4 v[170:173], v32, s[8:9]
	global_load_dwordx4 v[174:177], v33, s[10:11]
	v_add_u32_e32 v32, s4, v32
	v_add_u32_e32 v33, s5, v33
	global_load_dwordx4 v[178:181], v32, s[8:9]
	global_load_dwordx4 v[182:185], v33, s[10:11]
	v_add_u32_e32 v32, s4, v32
	v_add_u32_e32 v33, s5, v33
	global_load_dwordx4 v[186:189], v32, s[8:9]
	global_load_dwordx4 v[190:193], v33, s[10:11]
	v_add_u32_e32 v32, s4, v32
	v_add_u32_e32 v33, s5, v33
	s_waitcnt vmcnt(24)
	v_cvt_pk_bf16_f32 v28, v24, v25
	v_cvt_pk_bf16_f32 v29, v26, v27
	global_store_dwordx2 v34, v[28:29], s[12:13]
	v_add_u32_e32 v34, s43, v34
	v_fmac_f32_e32 v194, v24, v198
	v_fmac_f32_e32 v195, v25, v199
	v_fmac_f32_e32 v196, v26, v200
	v_fmac_f32_e32 v197, v27, v201
	v_cvt_pk_bf16_f32 v30, v194, v195
	v_cvt_pk_bf16_f32 v31, v196, v197
	global_store_dwordx2 v34, v[30:31], s[12:13]
	v_add_u32_e32 v34, s43, v34
	v_fmac_f32_e32 v202, v194, v206
	v_fmac_f32_e32 v203, v195, v207
	v_fmac_f32_e32 v204, v196, v208
	v_fmac_f32_e32 v205, v197, v209
	v_cvt_pk_bf16_f32 v28, v202, v203
	v_cvt_pk_bf16_f32 v29, v204, v205
	global_store_dwordx2 v34, v[28:29], s[12:13]
	v_add_u32_e32 v34, s43, v34
	v_fmac_f32_e32 v212, v202, v216
	v_fmac_f32_e32 v213, v203, v217
	v_fmac_f32_e32 v214, v204, v218
	v_fmac_f32_e32 v215, v205, v219
	v_cvt_pk_bf16_f32 v30, v212, v213
	v_cvt_pk_bf16_f32 v31, v214, v215
	global_store_dwordx2 v34, v[30:31], s[12:13]
	v_add_u32_e32 v34, s43, v34
	v_fmac_f32_e32 v220, v212, v224
	v_fmac_f32_e32 v221, v213, v225
	v_fmac_f32_e32 v222, v214, v226
	v_fmac_f32_e32 v223, v215, v227
	v_cvt_pk_bf16_f32 v28, v220, v221
	v_cvt_pk_bf16_f32 v29, v222, v223
	global_store_dwordx2 v34, v[28:29], s[12:13]
	v_add_u32_e32 v34, s43, v34
	v_fmac_f32_e32 v228, v220, v66
	v_fmac_f32_e32 v229, v221, v67
	v_fmac_f32_e32 v230, v222, v68
	v_fmac_f32_e32 v231, v223, v69
	v_cvt_pk_bf16_f32 v30, v228, v229
	v_cvt_pk_bf16_f32 v31, v230, v231
	global_store_dwordx2 v34, v[30:31], s[12:13]
	v_add_u32_e32 v34, s43, v34
	v_fmac_f32_e32 v70, v228, v74
	v_fmac_f32_e32 v71, v229, v75
	v_fmac_f32_e32 v72, v230, v76
	v_fmac_f32_e32 v73, v231, v77
	v_cvt_pk_bf16_f32 v28, v70, v71
	v_cvt_pk_bf16_f32 v29, v72, v73
	global_store_dwordx2 v34, v[28:29], s[12:13]
	v_add_u32_e32 v34, s43, v34
	v_fmac_f32_e32 v78, v70, v8
	v_fmac_f32_e32 v79, v71, v9
	v_fmac_f32_e32 v80, v72, v10
	v_fmac_f32_e32 v81, v73, v11
	v_cvt_pk_bf16_f32 v30, v78, v79
	v_cvt_pk_bf16_f32 v31, v80, v81
	global_store_dwordx2 v34, v[30:31], s[12:13]
	v_add_u32_e32 v34, s43, v34
	v_fmac_f32_e32 v12, v78, v16
	v_fmac_f32_e32 v13, v79, v17
	v_fmac_f32_e32 v14, v80, v18
	v_fmac_f32_e32 v15, v81, v19
	v_mov_b32_e32 v24, v12
	v_mov_b32_e32 v25, v13
	v_mov_b32_e32 v26, v14
	v_mov_b32_e32 v27, v15
	global_load_dwordx4 v[194:197], v32, s[8:9]
	global_load_dwordx4 v[198:201], v33, s[10:11]
	v_add_u32_e32 v32, s4, v32
	v_add_u32_e32 v33, s5, v33
	global_load_dwordx4 v[202:205], v32, s[8:9]
	global_load_dwordx4 v[206:209], v33, s[10:11]
	v_add_u32_e32 v32, s4, v32
	v_add_u32_e32 v33, s5, v33
	global_load_dwordx4 v[212:215], v32, s[8:9]
	global_load_dwordx4 v[216:219], v33, s[10:11]
	v_add_u32_e32 v32, s4, v32
	v_add_u32_e32 v33, s5, v33
	global_load_dwordx4 v[220:223], v32, s[8:9]
	global_load_dwordx4 v[224:227], v33, s[10:11]
	v_add_u32_e32 v32, s4, v32
	v_add_u32_e32 v33, s5, v33
	global_load_dwordx4 v[228:231], v32, s[8:9]
	global_load_dwordx4 v[66:69], v33, s[10:11]
	v_add_u32_e32 v32, s4, v32
	v_add_u32_e32 v33, s5, v33
	global_load_dwordx4 v[70:73], v32, s[8:9]
	global_load_dwordx4 v[74:77], v33, s[10:11]
	v_add_u32_e32 v32, s4, v32
	v_add_u32_e32 v33, s5, v33
	global_load_dwordx4 v[78:81], v32, s[8:9]
	global_load_dwordx4 v[8:11], v33, s[10:11]
	v_add_u32_e32 v32, s4, v32
	v_add_u32_e32 v33, s5, v33
	global_load_dwordx4 v[12:15], v32, s[8:9]
	global_load_dwordx4 v[16:19], v33, s[10:11]
	v_add_u32_e32 v32, s4, v32
	v_add_u32_e32 v33, s5, v33
	s_waitcnt vmcnt(24)
	v_cvt_pk_bf16_f32 v28, v24, v25
	v_cvt_pk_bf16_f32 v29, v26, v27
	global_store_dwordx2 v34, v[28:29], s[12:13]
	v_add_u32_e32 v34, s43, v34
	v_fmac_f32_e32 v130, v24, v134
	v_fmac_f32_e32 v131, v25, v135
	v_fmac_f32_e32 v132, v26, v136
	v_fmac_f32_e32 v133, v27, v137
	v_cvt_pk_bf16_f32 v30, v130, v131
	v_cvt_pk_bf16_f32 v31, v132, v133
	global_store_dwordx2 v34, v[30:31], s[12:13]
	v_add_u32_e32 v34, s43, v34
	v_fmac_f32_e32 v138, v130, v142
	v_fmac_f32_e32 v139, v131, v143
	v_fmac_f32_e32 v140, v132, v144
	v_fmac_f32_e32 v141, v133, v145
	v_cvt_pk_bf16_f32 v28, v138, v139
	v_cvt_pk_bf16_f32 v29, v140, v141
	global_store_dwordx2 v34, v[28:29], s[12:13]
	v_add_u32_e32 v34, s43, v34
	v_fmac_f32_e32 v146, v138, v150
	v_fmac_f32_e32 v147, v139, v151
	v_fmac_f32_e32 v148, v140, v152
	v_fmac_f32_e32 v149, v141, v153
	v_cvt_pk_bf16_f32 v30, v146, v147
	v_cvt_pk_bf16_f32 v31, v148, v149
	global_store_dwordx2 v34, v[30:31], s[12:13]
	v_add_u32_e32 v34, s43, v34
	v_fmac_f32_e32 v154, v146, v158
	v_fmac_f32_e32 v155, v147, v159
	v_fmac_f32_e32 v156, v148, v160
	v_fmac_f32_e32 v157, v149, v161
	v_cvt_pk_bf16_f32 v28, v154, v155
	v_cvt_pk_bf16_f32 v29, v156, v157
	global_store_dwordx2 v34, v[28:29], s[12:13]
	v_add_u32_e32 v34, s43, v34
	v_fmac_f32_e32 v162, v154, v166
	v_fmac_f32_e32 v163, v155, v167
	v_fmac_f32_e32 v164, v156, v168
	v_fmac_f32_e32 v165, v157, v169
	v_cvt_pk_bf16_f32 v30, v162, v163
	v_cvt_pk_bf16_f32 v31, v164, v165
	global_store_dwordx2 v34, v[30:31], s[12:13]
	v_add_u32_e32 v34, s43, v34
	v_fmac_f32_e32 v170, v162, v174
	v_fmac_f32_e32 v171, v163, v175
	v_fmac_f32_e32 v172, v164, v176
	v_fmac_f32_e32 v173, v165, v177
	v_cvt_pk_bf16_f32 v28, v170, v171
	v_cvt_pk_bf16_f32 v29, v172, v173
	global_store_dwordx2 v34, v[28:29], s[12:13]
	v_add_u32_e32 v34, s43, v34
	v_fmac_f32_e32 v178, v170, v182
	v_fmac_f32_e32 v179, v171, v183
	v_fmac_f32_e32 v180, v172, v184
	v_fmac_f32_e32 v181, v173, v185
	v_cvt_pk_bf16_f32 v30, v178, v179
	v_cvt_pk_bf16_f32 v31, v180, v181
	global_store_dwordx2 v34, v[30:31], s[12:13]
	v_add_u32_e32 v34, s43, v34
	v_fmac_f32_e32 v186, v178, v190
	v_fmac_f32_e32 v187, v179, v191
	v_fmac_f32_e32 v188, v180, v192
	v_fmac_f32_e32 v189, v181, v193
	v_mov_b32_e32 v24, v186
	v_mov_b32_e32 v25, v187
	v_mov_b32_e32 v26, v188
	v_mov_b32_e32 v27, v189
	global_load_dwordx4 v[130:133], v32, s[8:9]
	global_load_dwordx4 v[134:137], v33, s[10:11]
	v_add_u32_e32 v32, s4, v32
	v_add_u32_e32 v33, s5, v33
	global_load_dwordx4 v[138:141], v32, s[8:9]
	global_load_dwordx4 v[142:145], v33, s[10:11]
	v_add_u32_e32 v32, s4, v32
	v_add_u32_e32 v33, s5, v33
	global_load_dwordx4 v[146:149], v32, s[8:9]
	global_load_dwordx4 v[150:153], v33, s[10:11]
	v_add_u32_e32 v32, s4, v32
	v_add_u32_e32 v33, s5, v33
	global_load_dwordx4 v[154:157], v32, s[8:9]
	global_load_dwordx4 v[158:161], v33, s[10:11]
	v_add_u32_e32 v32, s4, v32
	v_add_u32_e32 v33, s5, v33
	global_load_dwordx4 v[162:165], v32, s[8:9]
	global_load_dwordx4 v[166:169], v33, s[10:11]
	v_add_u32_e32 v32, s4, v32
	v_add_u32_e32 v33, s5, v33
	global_load_dwordx4 v[170:173], v32, s[8:9]
	global_load_dwordx4 v[174:177], v33, s[10:11]
	v_add_u32_e32 v32, s4, v32
	v_add_u32_e32 v33, s5, v33
	global_load_dwordx4 v[178:181], v32, s[8:9]
	global_load_dwordx4 v[182:185], v33, s[10:11]
	v_add_u32_e32 v32, s4, v32
	v_add_u32_e32 v33, s5, v33
	global_load_dwordx4 v[186:189], v32, s[8:9]
	global_load_dwordx4 v[190:193], v33, s[10:11]
	v_add_u32_e32 v32, s4, v32
	v_add_u32_e32 v33, s5, v33
	s_waitcnt vmcnt(24)
	v_cvt_pk_bf16_f32 v28, v24, v25
	v_cvt_pk_bf16_f32 v29, v26, v27
	global_store_dwordx2 v34, v[28:29], s[12:13]
	v_add_u32_e32 v34, s43, v34
	v_fmac_f32_e32 v194, v24, v198
	v_fmac_f32_e32 v195, v25, v199
	v_fmac_f32_e32 v196, v26, v200
	v_fmac_f32_e32 v197, v27, v201
	v_cvt_pk_bf16_f32 v30, v194, v195
	v_cvt_pk_bf16_f32 v31, v196, v197
	global_store_dwordx2 v34, v[30:31], s[12:13]
	v_add_u32_e32 v34, s43, v34
	v_fmac_f32_e32 v202, v194, v206
	v_fmac_f32_e32 v203, v195, v207
	v_fmac_f32_e32 v204, v196, v208
	v_fmac_f32_e32 v205, v197, v209
	v_cvt_pk_bf16_f32 v28, v202, v203
	v_cvt_pk_bf16_f32 v29, v204, v205
	global_store_dwordx2 v34, v[28:29], s[12:13]
	v_add_u32_e32 v34, s43, v34
	v_fmac_f32_e32 v212, v202, v216
	v_fmac_f32_e32 v213, v203, v217
	v_fmac_f32_e32 v214, v204, v218
	v_fmac_f32_e32 v215, v205, v219
	v_cvt_pk_bf16_f32 v30, v212, v213
	v_cvt_pk_bf16_f32 v31, v214, v215
	global_store_dwordx2 v34, v[30:31], s[12:13]
	v_add_u32_e32 v34, s43, v34
	v_fmac_f32_e32 v220, v212, v224
	v_fmac_f32_e32 v221, v213, v225
	v_fmac_f32_e32 v222, v214, v226
	v_fmac_f32_e32 v223, v215, v227
	v_cvt_pk_bf16_f32 v28, v220, v221
	v_cvt_pk_bf16_f32 v29, v222, v223
	global_store_dwordx2 v34, v[28:29], s[12:13]
	v_add_u32_e32 v34, s43, v34
	v_fmac_f32_e32 v228, v220, v66
	v_fmac_f32_e32 v229, v221, v67
	v_fmac_f32_e32 v230, v222, v68
	v_fmac_f32_e32 v231, v223, v69
	v_cvt_pk_bf16_f32 v30, v228, v229
	v_cvt_pk_bf16_f32 v31, v230, v231
	global_store_dwordx2 v34, v[30:31], s[12:13]
	v_add_u32_e32 v34, s43, v34
	v_fmac_f32_e32 v70, v228, v74
	v_fmac_f32_e32 v71, v229, v75
	v_fmac_f32_e32 v72, v230, v76
	v_fmac_f32_e32 v73, v231, v77
	v_cvt_pk_bf16_f32 v28, v70, v71
	v_cvt_pk_bf16_f32 v29, v72, v73
	global_store_dwordx2 v34, v[28:29], s[12:13]
	v_add_u32_e32 v34, s43, v34
	v_fmac_f32_e32 v78, v70, v8
	v_fmac_f32_e32 v79, v71, v9
	v_fmac_f32_e32 v80, v72, v10
	v_fmac_f32_e32 v81, v73, v11
	v_cvt_pk_bf16_f32 v30, v78, v79
	v_cvt_pk_bf16_f32 v31, v80, v81
	global_store_dwordx2 v34, v[30:31], s[12:13]
	v_add_u32_e32 v34, s43, v34
	v_fmac_f32_e32 v12, v78, v16
	v_fmac_f32_e32 v13, v79, v17
	v_fmac_f32_e32 v14, v80, v18
	v_fmac_f32_e32 v15, v81, v19
	v_mov_b32_e32 v24, v12
	v_mov_b32_e32 v25, v13
	v_mov_b32_e32 v26, v14
	v_mov_b32_e32 v27, v15
	global_load_dwordx4 v[194:197], v32, s[8:9]
	global_load_dwordx4 v[198:201], v33, s[10:11]
	v_add_u32_e32 v32, s4, v32
	v_add_u32_e32 v33, s5, v33
	global_load_dwordx4 v[202:205], v32, s[8:9]
	global_load_dwordx4 v[206:209], v33, s[10:11]
	v_add_u32_e32 v32, s4, v32
	v_add_u32_e32 v33, s5, v33
	global_load_dwordx4 v[212:215], v32, s[8:9]
	global_load_dwordx4 v[216:219], v33, s[10:11]
	v_add_u32_e32 v32, s4, v32
	v_add_u32_e32 v33, s5, v33
	global_load_dwordx4 v[220:223], v32, s[8:9]
	global_load_dwordx4 v[224:227], v33, s[10:11]
	v_add_u32_e32 v32, s4, v32
	v_add_u32_e32 v33, s5, v33
	global_load_dwordx4 v[228:231], v32, s[8:9]
	global_load_dwordx4 v[66:69], v33, s[10:11]
	v_add_u32_e32 v32, s4, v32
	v_add_u32_e32 v33, s5, v33
	global_load_dwordx4 v[70:73], v32, s[8:9]
	global_load_dwordx4 v[74:77], v33, s[10:11]
	v_add_u32_e32 v32, s4, v32
	v_add_u32_e32 v33, s5, v33
	global_load_dwordx4 v[78:81], v32, s[8:9]
	global_load_dwordx4 v[8:11], v33, s[10:11]
	v_add_u32_e32 v32, s4, v32
	v_add_u32_e32 v33, s5, v33
	global_load_dwordx4 v[12:15], v32, s[8:9]
	global_load_dwordx4 v[16:19], v33, s[10:11]
	v_add_u32_e32 v32, s4, v32
	v_add_u32_e32 v33, s5, v33
	s_waitcnt vmcnt(24)
	v_cvt_pk_bf16_f32 v28, v24, v25
	v_cvt_pk_bf16_f32 v29, v26, v27
	global_store_dwordx2 v34, v[28:29], s[12:13]
	v_add_u32_e32 v34, s43, v34
	v_fmac_f32_e32 v130, v24, v134
	v_fmac_f32_e32 v131, v25, v135
	v_fmac_f32_e32 v132, v26, v136
	v_fmac_f32_e32 v133, v27, v137
	v_cvt_pk_bf16_f32 v30, v130, v131
	v_cvt_pk_bf16_f32 v31, v132, v133
	global_store_dwordx2 v34, v[30:31], s[12:13]
	v_add_u32_e32 v34, s43, v34
	v_fmac_f32_e32 v138, v130, v142
	v_fmac_f32_e32 v139, v131, v143
	v_fmac_f32_e32 v140, v132, v144
	v_fmac_f32_e32 v141, v133, v145
	v_cvt_pk_bf16_f32 v28, v138, v139
	v_cvt_pk_bf16_f32 v29, v140, v141
	global_store_dwordx2 v34, v[28:29], s[12:13]
	v_add_u32_e32 v34, s43, v34
	v_fmac_f32_e32 v146, v138, v150
	v_fmac_f32_e32 v147, v139, v151
	v_fmac_f32_e32 v148, v140, v152
	v_fmac_f32_e32 v149, v141, v153
	v_cvt_pk_bf16_f32 v30, v146, v147
	v_cvt_pk_bf16_f32 v31, v148, v149
	global_store_dwordx2 v34, v[30:31], s[12:13]
	v_add_u32_e32 v34, s43, v34
	v_fmac_f32_e32 v154, v146, v158
	v_fmac_f32_e32 v155, v147, v159
	v_fmac_f32_e32 v156, v148, v160
	v_fmac_f32_e32 v157, v149, v161
	v_cvt_pk_bf16_f32 v28, v154, v155
	v_cvt_pk_bf16_f32 v29, v156, v157
	global_store_dwordx2 v34, v[28:29], s[12:13]
	v_add_u32_e32 v34, s43, v34
	v_fmac_f32_e32 v162, v154, v166
	v_fmac_f32_e32 v163, v155, v167
	v_fmac_f32_e32 v164, v156, v168
	v_fmac_f32_e32 v165, v157, v169
	v_cvt_pk_bf16_f32 v30, v162, v163
	v_cvt_pk_bf16_f32 v31, v164, v165
	global_store_dwordx2 v34, v[30:31], s[12:13]
	v_add_u32_e32 v34, s43, v34
	v_fmac_f32_e32 v170, v162, v174
	v_fmac_f32_e32 v171, v163, v175
	v_fmac_f32_e32 v172, v164, v176
	v_fmac_f32_e32 v173, v165, v177
	v_cvt_pk_bf16_f32 v28, v170, v171
	v_cvt_pk_bf16_f32 v29, v172, v173
	global_store_dwordx2 v34, v[28:29], s[12:13]
	v_add_u32_e32 v34, s43, v34
	v_fmac_f32_e32 v178, v170, v182
	v_fmac_f32_e32 v179, v171, v183
	v_fmac_f32_e32 v180, v172, v184
	v_fmac_f32_e32 v181, v173, v185
	v_cvt_pk_bf16_f32 v30, v178, v179
	v_cvt_pk_bf16_f32 v31, v180, v181
	global_store_dwordx2 v34, v[30:31], s[12:13]
	v_add_u32_e32 v34, s43, v34
	v_fmac_f32_e32 v186, v178, v190
	v_fmac_f32_e32 v187, v179, v191
	v_fmac_f32_e32 v188, v180, v192
	v_fmac_f32_e32 v189, v181, v193
	v_mov_b32_e32 v24, v186
	v_mov_b32_e32 v25, v187
	v_mov_b32_e32 v26, v188
	v_mov_b32_e32 v27, v189
	global_load_dwordx4 v[130:133], v32, s[8:9]
	global_load_dwordx4 v[134:137], v33, s[10:11]
	v_add_u32_e32 v32, s4, v32
	v_add_u32_e32 v33, s5, v33
	global_load_dwordx4 v[138:141], v32, s[8:9]
	global_load_dwordx4 v[142:145], v33, s[10:11]
	v_add_u32_e32 v32, s4, v32
	v_add_u32_e32 v33, s5, v33
	global_load_dwordx4 v[146:149], v32, s[8:9]
	global_load_dwordx4 v[150:153], v33, s[10:11]
	v_add_u32_e32 v32, s4, v32
	v_add_u32_e32 v33, s5, v33
	global_load_dwordx4 v[154:157], v32, s[8:9]
	global_load_dwordx4 v[158:161], v33, s[10:11]
	v_add_u32_e32 v32, s4, v32
	v_add_u32_e32 v33, s5, v33
	global_load_dwordx4 v[162:165], v32, s[8:9]
	global_load_dwordx4 v[166:169], v33, s[10:11]
	v_add_u32_e32 v32, s4, v32
	v_add_u32_e32 v33, s5, v33
	global_load_dwordx4 v[170:173], v32, s[8:9]
	global_load_dwordx4 v[174:177], v33, s[10:11]
	v_add_u32_e32 v32, s4, v32
	v_add_u32_e32 v33, s5, v33
	global_load_dwordx4 v[178:181], v32, s[8:9]
	global_load_dwordx4 v[182:185], v33, s[10:11]
	v_add_u32_e32 v32, s4, v32
	v_add_u32_e32 v33, s5, v33
	global_load_dwordx4 v[186:189], v32, s[8:9]
	global_load_dwordx4 v[190:193], v33, s[10:11]
	v_add_u32_e32 v32, s4, v32
	v_add_u32_e32 v33, s5, v33
	s_waitcnt vmcnt(24)
	v_cvt_pk_bf16_f32 v28, v24, v25
	v_cvt_pk_bf16_f32 v29, v26, v27
	global_store_dwordx2 v34, v[28:29], s[12:13]
	v_add_u32_e32 v34, s43, v34
	v_fmac_f32_e32 v194, v24, v198
	v_fmac_f32_e32 v195, v25, v199
	v_fmac_f32_e32 v196, v26, v200
	v_fmac_f32_e32 v197, v27, v201
	v_cvt_pk_bf16_f32 v30, v194, v195
	v_cvt_pk_bf16_f32 v31, v196, v197
	global_store_dwordx2 v34, v[30:31], s[12:13]
	v_add_u32_e32 v34, s43, v34
	v_fmac_f32_e32 v202, v194, v206
	v_fmac_f32_e32 v203, v195, v207
	v_fmac_f32_e32 v204, v196, v208
	v_fmac_f32_e32 v205, v197, v209
	v_cvt_pk_bf16_f32 v28, v202, v203
	v_cvt_pk_bf16_f32 v29, v204, v205
	global_store_dwordx2 v34, v[28:29], s[12:13]
	v_add_u32_e32 v34, s43, v34
	v_fmac_f32_e32 v212, v202, v216
	v_fmac_f32_e32 v213, v203, v217
	v_fmac_f32_e32 v214, v204, v218
	v_fmac_f32_e32 v215, v205, v219
	v_cvt_pk_bf16_f32 v30, v212, v213
	v_cvt_pk_bf16_f32 v31, v214, v215
	global_store_dwordx2 v34, v[30:31], s[12:13]
	v_add_u32_e32 v34, s43, v34
	v_fmac_f32_e32 v220, v212, v224
	v_fmac_f32_e32 v221, v213, v225
	v_fmac_f32_e32 v222, v214, v226
	v_fmac_f32_e32 v223, v215, v227
	v_cvt_pk_bf16_f32 v28, v220, v221
	v_cvt_pk_bf16_f32 v29, v222, v223
	global_store_dwordx2 v34, v[28:29], s[12:13]
	v_add_u32_e32 v34, s43, v34
	v_fmac_f32_e32 v228, v220, v66
	v_fmac_f32_e32 v229, v221, v67
	v_fmac_f32_e32 v230, v222, v68
	v_fmac_f32_e32 v231, v223, v69
	v_cvt_pk_bf16_f32 v30, v228, v229
	v_cvt_pk_bf16_f32 v31, v230, v231
	global_store_dwordx2 v34, v[30:31], s[12:13]
	v_add_u32_e32 v34, s43, v34
	v_fmac_f32_e32 v70, v228, v74
	v_fmac_f32_e32 v71, v229, v75
	v_fmac_f32_e32 v72, v230, v76
	v_fmac_f32_e32 v73, v231, v77
	v_cvt_pk_bf16_f32 v28, v70, v71
	v_cvt_pk_bf16_f32 v29, v72, v73
	global_store_dwordx2 v34, v[28:29], s[12:13]
	v_add_u32_e32 v34, s43, v34
	v_fmac_f32_e32 v78, v70, v8
	v_fmac_f32_e32 v79, v71, v9
	v_fmac_f32_e32 v80, v72, v10
	v_fmac_f32_e32 v81, v73, v11
	v_cvt_pk_bf16_f32 v30, v78, v79
	v_cvt_pk_bf16_f32 v31, v80, v81
	global_store_dwordx2 v34, v[30:31], s[12:13]
	v_add_u32_e32 v34, s43, v34
	v_fmac_f32_e32 v12, v78, v16
	v_fmac_f32_e32 v13, v79, v17
	v_fmac_f32_e32 v14, v80, v18
	v_fmac_f32_e32 v15, v81, v19
	v_mov_b32_e32 v24, v12
	v_mov_b32_e32 v25, v13
	v_mov_b32_e32 v26, v14
	v_mov_b32_e32 v27, v15
	global_load_dwordx4 v[194:197], v32, s[8:9]
	global_load_dwordx4 v[198:201], v33, s[10:11]
	v_add_u32_e32 v32, s4, v32
	v_add_u32_e32 v33, s5, v33
	global_load_dwordx4 v[202:205], v32, s[8:9]
	global_load_dwordx4 v[206:209], v33, s[10:11]
	v_add_u32_e32 v32, s4, v32
	v_add_u32_e32 v33, s5, v33
	global_load_dwordx4 v[212:215], v32, s[8:9]
	global_load_dwordx4 v[216:219], v33, s[10:11]
	v_add_u32_e32 v32, s4, v32
	v_add_u32_e32 v33, s5, v33
	global_load_dwordx4 v[220:223], v32, s[8:9]
	global_load_dwordx4 v[224:227], v33, s[10:11]
	v_add_u32_e32 v32, s4, v32
	v_add_u32_e32 v33, s5, v33
	global_load_dwordx4 v[228:231], v32, s[8:9]
	global_load_dwordx4 v[66:69], v33, s[10:11]
	v_add_u32_e32 v32, s4, v32
	v_add_u32_e32 v33, s5, v33
	global_load_dwordx4 v[70:73], v32, s[8:9]
	global_load_dwordx4 v[74:77], v33, s[10:11]
	v_add_u32_e32 v32, s4, v32
	v_add_u32_e32 v33, s5, v33
	global_load_dwordx4 v[78:81], v32, s[8:9]
	global_load_dwordx4 v[8:11], v33, s[10:11]
	v_add_u32_e32 v32, s4, v32
	v_add_u32_e32 v33, s5, v33
	global_load_dwordx4 v[12:15], v32, s[8:9]
	global_load_dwordx4 v[16:19], v33, s[10:11]
	v_add_u32_e32 v32, s4, v32
	v_add_u32_e32 v33, s5, v33
	s_waitcnt vmcnt(24)
	v_cvt_pk_bf16_f32 v28, v24, v25
	v_cvt_pk_bf16_f32 v29, v26, v27
	global_store_dwordx2 v34, v[28:29], s[12:13]
	v_add_u32_e32 v34, s43, v34
	v_fmac_f32_e32 v130, v24, v134
	v_fmac_f32_e32 v131, v25, v135
	v_fmac_f32_e32 v132, v26, v136
	v_fmac_f32_e32 v133, v27, v137
	v_cvt_pk_bf16_f32 v30, v130, v131
	v_cvt_pk_bf16_f32 v31, v132, v133
	global_store_dwordx2 v34, v[30:31], s[12:13]
	v_add_u32_e32 v34, s43, v34
	v_fmac_f32_e32 v138, v130, v142
	v_fmac_f32_e32 v139, v131, v143
	v_fmac_f32_e32 v140, v132, v144
	v_fmac_f32_e32 v141, v133, v145
	v_cvt_pk_bf16_f32 v28, v138, v139
	v_cvt_pk_bf16_f32 v29, v140, v141
	global_store_dwordx2 v34, v[28:29], s[12:13]
	v_add_u32_e32 v34, s43, v34
	v_fmac_f32_e32 v146, v138, v150
	v_fmac_f32_e32 v147, v139, v151
	v_fmac_f32_e32 v148, v140, v152
	v_fmac_f32_e32 v149, v141, v153
	v_cvt_pk_bf16_f32 v30, v146, v147
	v_cvt_pk_bf16_f32 v31, v148, v149
	global_store_dwordx2 v34, v[30:31], s[12:13]
	v_add_u32_e32 v34, s43, v34
	v_fmac_f32_e32 v154, v146, v158
	v_fmac_f32_e32 v155, v147, v159
	v_fmac_f32_e32 v156, v148, v160
	v_fmac_f32_e32 v157, v149, v161
	v_cvt_pk_bf16_f32 v28, v154, v155
	v_cvt_pk_bf16_f32 v29, v156, v157
	global_store_dwordx2 v34, v[28:29], s[12:13]
	v_add_u32_e32 v34, s43, v34
	v_fmac_f32_e32 v162, v154, v166
	v_fmac_f32_e32 v163, v155, v167
	v_fmac_f32_e32 v164, v156, v168
	v_fmac_f32_e32 v165, v157, v169
	v_cvt_pk_bf16_f32 v30, v162, v163
	v_cvt_pk_bf16_f32 v31, v164, v165
	global_store_dwordx2 v34, v[30:31], s[12:13]
	v_add_u32_e32 v34, s43, v34
	v_fmac_f32_e32 v170, v162, v174
	v_fmac_f32_e32 v171, v163, v175
	v_fmac_f32_e32 v172, v164, v176
	v_fmac_f32_e32 v173, v165, v177
	v_cvt_pk_bf16_f32 v28, v170, v171
	v_cvt_pk_bf16_f32 v29, v172, v173
	global_store_dwordx2 v34, v[28:29], s[12:13]
	v_add_u32_e32 v34, s43, v34
	v_fmac_f32_e32 v178, v170, v182
	v_fmac_f32_e32 v179, v171, v183
	v_fmac_f32_e32 v180, v172, v184
	v_fmac_f32_e32 v181, v173, v185
	v_cvt_pk_bf16_f32 v30, v178, v179
	v_cvt_pk_bf16_f32 v31, v180, v181
	global_store_dwordx2 v34, v[30:31], s[12:13]
	v_add_u32_e32 v34, s43, v34
	v_fmac_f32_e32 v186, v178, v190
	v_fmac_f32_e32 v187, v179, v191
	v_fmac_f32_e32 v188, v180, v192
	v_fmac_f32_e32 v189, v181, v193
	v_mov_b32_e32 v24, v186
	v_mov_b32_e32 v25, v187
	v_mov_b32_e32 v26, v188
	v_mov_b32_e32 v27, v189
	global_load_dwordx4 v[130:133], v32, s[8:9]
	global_load_dwordx4 v[134:137], v33, s[10:11]
	v_add_u32_e32 v32, s4, v32
	v_add_u32_e32 v33, s5, v33
	global_load_dwordx4 v[138:141], v32, s[8:9]
	global_load_dwordx4 v[142:145], v33, s[10:11]
	v_add_u32_e32 v32, s4, v32
	v_add_u32_e32 v33, s5, v33
	global_load_dwordx4 v[146:149], v32, s[8:9]
	global_load_dwordx4 v[150:153], v33, s[10:11]
	v_add_u32_e32 v32, s4, v32
	v_add_u32_e32 v33, s5, v33
	global_load_dwordx4 v[154:157], v32, s[8:9]
	global_load_dwordx4 v[158:161], v33, s[10:11]
	v_add_u32_e32 v32, s4, v32
	v_add_u32_e32 v33, s5, v33
	global_load_dwordx4 v[162:165], v32, s[8:9]
	global_load_dwordx4 v[166:169], v33, s[10:11]
	v_add_u32_e32 v32, s4, v32
	v_add_u32_e32 v33, s5, v33
	global_load_dwordx4 v[170:173], v32, s[8:9]
	global_load_dwordx4 v[174:177], v33, s[10:11]
	v_add_u32_e32 v32, s4, v32
	v_add_u32_e32 v33, s5, v33
	global_load_dwordx4 v[178:181], v32, s[8:9]
	global_load_dwordx4 v[182:185], v33, s[10:11]
	v_add_u32_e32 v32, s4, v32
	v_add_u32_e32 v33, s5, v33
	global_load_dwordx4 v[186:189], v32, s[8:9]
	global_load_dwordx4 v[190:193], v33, s[10:11]
	v_add_u32_e32 v32, s4, v32
	v_add_u32_e32 v33, s5, v33
	s_waitcnt vmcnt(24)
	v_cvt_pk_bf16_f32 v28, v24, v25
	v_cvt_pk_bf16_f32 v29, v26, v27
	global_store_dwordx2 v34, v[28:29], s[12:13]
	v_add_u32_e32 v34, s43, v34
	v_fmac_f32_e32 v194, v24, v198
	v_fmac_f32_e32 v195, v25, v199
	v_fmac_f32_e32 v196, v26, v200
	v_fmac_f32_e32 v197, v27, v201
	v_cvt_pk_bf16_f32 v30, v194, v195
	v_cvt_pk_bf16_f32 v31, v196, v197
	global_store_dwordx2 v34, v[30:31], s[12:13]
	v_add_u32_e32 v34, s43, v34
	v_fmac_f32_e32 v202, v194, v206
	v_fmac_f32_e32 v203, v195, v207
	v_fmac_f32_e32 v204, v196, v208
	v_fmac_f32_e32 v205, v197, v209
	v_cvt_pk_bf16_f32 v28, v202, v203
	v_cvt_pk_bf16_f32 v29, v204, v205
	global_store_dwordx2 v34, v[28:29], s[12:13]
	v_add_u32_e32 v34, s43, v34
	v_fmac_f32_e32 v212, v202, v216
	v_fmac_f32_e32 v213, v203, v217
	v_fmac_f32_e32 v214, v204, v218
	v_fmac_f32_e32 v215, v205, v219
	v_cvt_pk_bf16_f32 v30, v212, v213
	v_cvt_pk_bf16_f32 v31, v214, v215
	global_store_dwordx2 v34, v[30:31], s[12:13]
	v_add_u32_e32 v34, s43, v34
	v_fmac_f32_e32 v220, v212, v224
	v_fmac_f32_e32 v221, v213, v225
	v_fmac_f32_e32 v222, v214, v226
	v_fmac_f32_e32 v223, v215, v227
	v_cvt_pk_bf16_f32 v28, v220, v221
	v_cvt_pk_bf16_f32 v29, v222, v223
	global_store_dwordx2 v34, v[28:29], s[12:13]
	v_add_u32_e32 v34, s43, v34
	v_fmac_f32_e32 v228, v220, v66
	v_fmac_f32_e32 v229, v221, v67
	v_fmac_f32_e32 v230, v222, v68
	v_fmac_f32_e32 v231, v223, v69
	v_cvt_pk_bf16_f32 v30, v228, v229
	v_cvt_pk_bf16_f32 v31, v230, v231
	global_store_dwordx2 v34, v[30:31], s[12:13]
	v_add_u32_e32 v34, s43, v34
	v_fmac_f32_e32 v70, v228, v74
	v_fmac_f32_e32 v71, v229, v75
	v_fmac_f32_e32 v72, v230, v76
	v_fmac_f32_e32 v73, v231, v77
	v_cvt_pk_bf16_f32 v28, v70, v71
	v_cvt_pk_bf16_f32 v29, v72, v73
	global_store_dwordx2 v34, v[28:29], s[12:13]
	v_add_u32_e32 v34, s43, v34
	v_fmac_f32_e32 v78, v70, v8
	v_fmac_f32_e32 v79, v71, v9
	v_fmac_f32_e32 v80, v72, v10
	v_fmac_f32_e32 v81, v73, v11
	v_cvt_pk_bf16_f32 v30, v78, v79
	v_cvt_pk_bf16_f32 v31, v80, v81
	global_store_dwordx2 v34, v[30:31], s[12:13]
	v_add_u32_e32 v34, s43, v34
	v_fmac_f32_e32 v12, v78, v16
	v_fmac_f32_e32 v13, v79, v17
	v_fmac_f32_e32 v14, v80, v18
	v_fmac_f32_e32 v15, v81, v19
	v_mov_b32_e32 v24, v12
	v_mov_b32_e32 v25, v13
	v_mov_b32_e32 v26, v14
	v_mov_b32_e32 v27, v15
	global_load_dwordx4 v[194:197], v32, s[8:9]
	global_load_dwordx4 v[198:201], v33, s[10:11]
	v_add_u32_e32 v32, s4, v32
	v_add_u32_e32 v33, s5, v33
	global_load_dwordx4 v[202:205], v32, s[8:9]
	global_load_dwordx4 v[206:209], v33, s[10:11]
	v_add_u32_e32 v32, s4, v32
	v_add_u32_e32 v33, s5, v33
	global_load_dwordx4 v[212:215], v32, s[8:9]
	global_load_dwordx4 v[216:219], v33, s[10:11]
	v_add_u32_e32 v32, s4, v32
	v_add_u32_e32 v33, s5, v33
	global_load_dwordx4 v[220:223], v32, s[8:9]
	global_load_dwordx4 v[224:227], v33, s[10:11]
	v_add_u32_e32 v32, s4, v32
	v_add_u32_e32 v33, s5, v33
	global_load_dwordx4 v[228:231], v32, s[8:9]
	global_load_dwordx4 v[66:69], v33, s[10:11]
	v_add_u32_e32 v32, s4, v32
	v_add_u32_e32 v33, s5, v33
	global_load_dwordx4 v[70:73], v32, s[8:9]
	global_load_dwordx4 v[74:77], v33, s[10:11]
	v_add_u32_e32 v32, s4, v32
	v_add_u32_e32 v33, s5, v33
	global_load_dwordx4 v[78:81], v32, s[8:9]
	global_load_dwordx4 v[8:11], v33, s[10:11]
	v_add_u32_e32 v32, s4, v32
	v_add_u32_e32 v33, s5, v33
	global_load_dwordx4 v[12:15], v32, s[8:9]
	global_load_dwordx4 v[16:19], v33, s[10:11]
	v_add_u32_e32 v32, s4, v32
	v_add_u32_e32 v33, s5, v33
	s_waitcnt vmcnt(24)
	v_cvt_pk_bf16_f32 v28, v24, v25
	v_cvt_pk_bf16_f32 v29, v26, v27
	global_store_dwordx2 v34, v[28:29], s[12:13]
	v_add_u32_e32 v34, s43, v34
	v_fmac_f32_e32 v130, v24, v134
	v_fmac_f32_e32 v131, v25, v135
	v_fmac_f32_e32 v132, v26, v136
	v_fmac_f32_e32 v133, v27, v137
	v_cvt_pk_bf16_f32 v30, v130, v131
	v_cvt_pk_bf16_f32 v31, v132, v133
	global_store_dwordx2 v34, v[30:31], s[12:13]
	v_add_u32_e32 v34, s43, v34
	v_fmac_f32_e32 v138, v130, v142
	v_fmac_f32_e32 v139, v131, v143
	v_fmac_f32_e32 v140, v132, v144
	v_fmac_f32_e32 v141, v133, v145
	v_cvt_pk_bf16_f32 v28, v138, v139
	v_cvt_pk_bf16_f32 v29, v140, v141
	global_store_dwordx2 v34, v[28:29], s[12:13]
	v_add_u32_e32 v34, s43, v34
	v_fmac_f32_e32 v146, v138, v150
	v_fmac_f32_e32 v147, v139, v151
	v_fmac_f32_e32 v148, v140, v152
	v_fmac_f32_e32 v149, v141, v153
	v_cvt_pk_bf16_f32 v30, v146, v147
	v_cvt_pk_bf16_f32 v31, v148, v149
	global_store_dwordx2 v34, v[30:31], s[12:13]
	v_add_u32_e32 v34, s43, v34
	v_fmac_f32_e32 v154, v146, v158
	v_fmac_f32_e32 v155, v147, v159
	v_fmac_f32_e32 v156, v148, v160
	v_fmac_f32_e32 v157, v149, v161
	v_cvt_pk_bf16_f32 v28, v154, v155
	v_cvt_pk_bf16_f32 v29, v156, v157
	global_store_dwordx2 v34, v[28:29], s[12:13]
	v_add_u32_e32 v34, s43, v34
	v_fmac_f32_e32 v162, v154, v166
	v_fmac_f32_e32 v163, v155, v167
	v_fmac_f32_e32 v164, v156, v168
	v_fmac_f32_e32 v165, v157, v169
	v_cvt_pk_bf16_f32 v30, v162, v163
	v_cvt_pk_bf16_f32 v31, v164, v165
	global_store_dwordx2 v34, v[30:31], s[12:13]
	v_add_u32_e32 v34, s43, v34
	v_fmac_f32_e32 v170, v162, v174
	v_fmac_f32_e32 v171, v163, v175
	v_fmac_f32_e32 v172, v164, v176
	v_fmac_f32_e32 v173, v165, v177
	v_cvt_pk_bf16_f32 v28, v170, v171
	v_cvt_pk_bf16_f32 v29, v172, v173
	global_store_dwordx2 v34, v[28:29], s[12:13]
	v_add_u32_e32 v34, s43, v34
	v_fmac_f32_e32 v178, v170, v182
	v_fmac_f32_e32 v179, v171, v183
	v_fmac_f32_e32 v180, v172, v184
	v_fmac_f32_e32 v181, v173, v185
	v_cvt_pk_bf16_f32 v30, v178, v179
	v_cvt_pk_bf16_f32 v31, v180, v181
	global_store_dwordx2 v34, v[30:31], s[12:13]
	v_add_u32_e32 v34, s43, v34
	v_fmac_f32_e32 v186, v178, v190
	v_fmac_f32_e32 v187, v179, v191
	v_fmac_f32_e32 v188, v180, v192
	v_fmac_f32_e32 v189, v181, v193
	v_mov_b32_e32 v24, v186
	v_mov_b32_e32 v25, v187
	v_mov_b32_e32 v26, v188
	v_mov_b32_e32 v27, v189
	global_load_dwordx4 v[130:133], v32, s[8:9]
	global_load_dwordx4 v[134:137], v33, s[10:11]
	v_add_u32_e32 v32, s4, v32
	v_add_u32_e32 v33, s5, v33
	global_load_dwordx4 v[138:141], v32, s[8:9]
	global_load_dwordx4 v[142:145], v33, s[10:11]
	v_add_u32_e32 v32, s4, v32
	v_add_u32_e32 v33, s5, v33
	global_load_dwordx4 v[146:149], v32, s[8:9]
	global_load_dwordx4 v[150:153], v33, s[10:11]
	v_add_u32_e32 v32, s4, v32
	v_add_u32_e32 v33, s5, v33
	global_load_dwordx4 v[154:157], v32, s[8:9]
	global_load_dwordx4 v[158:161], v33, s[10:11]
	v_add_u32_e32 v32, s4, v32
	v_add_u32_e32 v33, s5, v33
	global_load_dwordx4 v[162:165], v32, s[8:9]
	global_load_dwordx4 v[166:169], v33, s[10:11]
	v_add_u32_e32 v32, s4, v32
	v_add_u32_e32 v33, s5, v33
	global_load_dwordx4 v[170:173], v32, s[8:9]
	global_load_dwordx4 v[174:177], v33, s[10:11]
	v_add_u32_e32 v32, s4, v32
	v_add_u32_e32 v33, s5, v33
	global_load_dwordx4 v[178:181], v32, s[8:9]
	global_load_dwordx4 v[182:185], v33, s[10:11]
	v_add_u32_e32 v32, s4, v32
	v_add_u32_e32 v33, s5, v33
	global_load_dwordx4 v[186:189], v32, s[8:9]
	global_load_dwordx4 v[190:193], v33, s[10:11]
	v_add_u32_e32 v32, s4, v32
	v_add_u32_e32 v33, s5, v33
	s_waitcnt vmcnt(24)
	v_cvt_pk_bf16_f32 v28, v24, v25
	v_cvt_pk_bf16_f32 v29, v26, v27
	global_store_dwordx2 v34, v[28:29], s[12:13]
	v_add_u32_e32 v34, s43, v34
	v_fmac_f32_e32 v194, v24, v198
	v_fmac_f32_e32 v195, v25, v199
	v_fmac_f32_e32 v196, v26, v200
	v_fmac_f32_e32 v197, v27, v201
	v_cvt_pk_bf16_f32 v30, v194, v195
	v_cvt_pk_bf16_f32 v31, v196, v197
	global_store_dwordx2 v34, v[30:31], s[12:13]
	v_add_u32_e32 v34, s43, v34
	v_fmac_f32_e32 v202, v194, v206
	v_fmac_f32_e32 v203, v195, v207
	v_fmac_f32_e32 v204, v196, v208
	v_fmac_f32_e32 v205, v197, v209
	v_cvt_pk_bf16_f32 v28, v202, v203
	v_cvt_pk_bf16_f32 v29, v204, v205
	global_store_dwordx2 v34, v[28:29], s[12:13]
	v_add_u32_e32 v34, s43, v34
	v_fmac_f32_e32 v212, v202, v216
	v_fmac_f32_e32 v213, v203, v217
	v_fmac_f32_e32 v214, v204, v218
	v_fmac_f32_e32 v215, v205, v219
	v_cvt_pk_bf16_f32 v30, v212, v213
	v_cvt_pk_bf16_f32 v31, v214, v215
	global_store_dwordx2 v34, v[30:31], s[12:13]
	v_add_u32_e32 v34, s43, v34
	v_fmac_f32_e32 v220, v212, v224
	v_fmac_f32_e32 v221, v213, v225
	v_fmac_f32_e32 v222, v214, v226
	v_fmac_f32_e32 v223, v215, v227
	v_cvt_pk_bf16_f32 v28, v220, v221
	v_cvt_pk_bf16_f32 v29, v222, v223
	global_store_dwordx2 v34, v[28:29], s[12:13]
	v_add_u32_e32 v34, s43, v34
	v_fmac_f32_e32 v228, v220, v66
	v_fmac_f32_e32 v229, v221, v67
	v_fmac_f32_e32 v230, v222, v68
	v_fmac_f32_e32 v231, v223, v69
	v_cvt_pk_bf16_f32 v30, v228, v229
	v_cvt_pk_bf16_f32 v31, v230, v231
	global_store_dwordx2 v34, v[30:31], s[12:13]
	v_add_u32_e32 v34, s43, v34
	v_fmac_f32_e32 v70, v228, v74
	v_fmac_f32_e32 v71, v229, v75
	v_fmac_f32_e32 v72, v230, v76
	v_fmac_f32_e32 v73, v231, v77
	v_cvt_pk_bf16_f32 v28, v70, v71
	v_cvt_pk_bf16_f32 v29, v72, v73
	global_store_dwordx2 v34, v[28:29], s[12:13]
	v_add_u32_e32 v34, s43, v34
	v_fmac_f32_e32 v78, v70, v8
	v_fmac_f32_e32 v79, v71, v9
	v_fmac_f32_e32 v80, v72, v10
	v_fmac_f32_e32 v81, v73, v11
	v_cvt_pk_bf16_f32 v30, v78, v79
	v_cvt_pk_bf16_f32 v31, v80, v81
	global_store_dwordx2 v34, v[30:31], s[12:13]
	v_add_u32_e32 v34, s43, v34
	v_fmac_f32_e32 v12, v78, v16
	v_fmac_f32_e32 v13, v79, v17
	v_fmac_f32_e32 v14, v80, v18
	v_fmac_f32_e32 v15, v81, v19
	v_mov_b32_e32 v24, v12
	v_mov_b32_e32 v25, v13
	v_mov_b32_e32 v26, v14
	v_mov_b32_e32 v27, v15
	global_load_dwordx4 v[194:197], v32, s[8:9]
	global_load_dwordx4 v[198:201], v33, s[10:11]
	v_add_u32_e32 v32, s4, v32
	v_add_u32_e32 v33, s5, v33
	global_load_dwordx4 v[202:205], v32, s[8:9]
	global_load_dwordx4 v[206:209], v33, s[10:11]
	v_add_u32_e32 v32, s4, v32
	v_add_u32_e32 v33, s5, v33
	global_load_dwordx4 v[212:215], v32, s[8:9]
	global_load_dwordx4 v[216:219], v33, s[10:11]
	v_add_u32_e32 v32, s4, v32
	v_add_u32_e32 v33, s5, v33
	global_load_dwordx4 v[220:223], v32, s[8:9]
	global_load_dwordx4 v[224:227], v33, s[10:11]
	v_add_u32_e32 v32, s4, v32
	v_add_u32_e32 v33, s5, v33
	global_load_dwordx4 v[228:231], v32, s[8:9]
	global_load_dwordx4 v[66:69], v33, s[10:11]
	v_add_u32_e32 v32, s4, v32
	v_add_u32_e32 v33, s5, v33
	global_load_dwordx4 v[70:73], v32, s[8:9]
	global_load_dwordx4 v[74:77], v33, s[10:11]
	v_add_u32_e32 v32, s4, v32
	v_add_u32_e32 v33, s5, v33
	global_load_dwordx4 v[78:81], v32, s[8:9]
	global_load_dwordx4 v[8:11], v33, s[10:11]
	v_add_u32_e32 v32, s4, v32
	v_add_u32_e32 v33, s5, v33
	global_load_dwordx4 v[12:15], v32, s[8:9]
	global_load_dwordx4 v[16:19], v33, s[10:11]
	v_add_u32_e32 v32, s4, v32
	v_add_u32_e32 v33, s5, v33
	s_waitcnt vmcnt(24)
	v_cvt_pk_bf16_f32 v28, v24, v25
	v_cvt_pk_bf16_f32 v29, v26, v27
	global_store_dwordx2 v34, v[28:29], s[12:13]
	v_add_u32_e32 v34, s43, v34
	v_fmac_f32_e32 v130, v24, v134
	v_fmac_f32_e32 v131, v25, v135
	v_fmac_f32_e32 v132, v26, v136
	v_fmac_f32_e32 v133, v27, v137
	v_cvt_pk_bf16_f32 v30, v130, v131
	v_cvt_pk_bf16_f32 v31, v132, v133
	global_store_dwordx2 v34, v[30:31], s[12:13]
	v_add_u32_e32 v34, s43, v34
	v_fmac_f32_e32 v138, v130, v142
	v_fmac_f32_e32 v139, v131, v143
	v_fmac_f32_e32 v140, v132, v144
	v_fmac_f32_e32 v141, v133, v145
	v_cvt_pk_bf16_f32 v28, v138, v139
	v_cvt_pk_bf16_f32 v29, v140, v141
	global_store_dwordx2 v34, v[28:29], s[12:13]
	v_add_u32_e32 v34, s43, v34
	v_fmac_f32_e32 v146, v138, v150
	v_fmac_f32_e32 v147, v139, v151
	v_fmac_f32_e32 v148, v140, v152
	v_fmac_f32_e32 v149, v141, v153
	v_cvt_pk_bf16_f32 v30, v146, v147
	v_cvt_pk_bf16_f32 v31, v148, v149
	global_store_dwordx2 v34, v[30:31], s[12:13]
	v_add_u32_e32 v34, s43, v34
	v_fmac_f32_e32 v154, v146, v158
	v_fmac_f32_e32 v155, v147, v159
	v_fmac_f32_e32 v156, v148, v160
	v_fmac_f32_e32 v157, v149, v161
	v_cvt_pk_bf16_f32 v28, v154, v155
	v_cvt_pk_bf16_f32 v29, v156, v157
	global_store_dwordx2 v34, v[28:29], s[12:13]
	v_add_u32_e32 v34, s43, v34
	v_fmac_f32_e32 v162, v154, v166
	v_fmac_f32_e32 v163, v155, v167
	v_fmac_f32_e32 v164, v156, v168
	v_fmac_f32_e32 v165, v157, v169
	v_cvt_pk_bf16_f32 v30, v162, v163
	v_cvt_pk_bf16_f32 v31, v164, v165
	global_store_dwordx2 v34, v[30:31], s[12:13]
	v_add_u32_e32 v34, s43, v34
	v_fmac_f32_e32 v170, v162, v174
	v_fmac_f32_e32 v171, v163, v175
	v_fmac_f32_e32 v172, v164, v176
	v_fmac_f32_e32 v173, v165, v177
	v_cvt_pk_bf16_f32 v28, v170, v171
	v_cvt_pk_bf16_f32 v29, v172, v173
	global_store_dwordx2 v34, v[28:29], s[12:13]
	v_add_u32_e32 v34, s43, v34
	v_fmac_f32_e32 v178, v170, v182
	v_fmac_f32_e32 v179, v171, v183
	v_fmac_f32_e32 v180, v172, v184
	v_fmac_f32_e32 v181, v173, v185
	v_cvt_pk_bf16_f32 v30, v178, v179
	v_cvt_pk_bf16_f32 v31, v180, v181
	global_store_dwordx2 v34, v[30:31], s[12:13]
	v_add_u32_e32 v34, s43, v34
	v_fmac_f32_e32 v186, v178, v190
	v_fmac_f32_e32 v187, v179, v191
	v_fmac_f32_e32 v188, v180, v192
	v_fmac_f32_e32 v189, v181, v193
	v_mov_b32_e32 v24, v186
	v_mov_b32_e32 v25, v187
	v_mov_b32_e32 v26, v188
	v_mov_b32_e32 v27, v189
	global_load_dwordx4 v[130:133], v32, s[8:9]
	global_load_dwordx4 v[134:137], v33, s[10:11]
	v_add_u32_e32 v32, s4, v32
	v_add_u32_e32 v33, s5, v33
	global_load_dwordx4 v[138:141], v32, s[8:9]
	global_load_dwordx4 v[142:145], v33, s[10:11]
	v_add_u32_e32 v32, s4, v32
	v_add_u32_e32 v33, s5, v33
	global_load_dwordx4 v[146:149], v32, s[8:9]
	global_load_dwordx4 v[150:153], v33, s[10:11]
	v_add_u32_e32 v32, s4, v32
	v_add_u32_e32 v33, s5, v33
	global_load_dwordx4 v[154:157], v32, s[8:9]
	global_load_dwordx4 v[158:161], v33, s[10:11]
	v_add_u32_e32 v32, s4, v32
	v_add_u32_e32 v33, s5, v33
	global_load_dwordx4 v[162:165], v32, s[8:9]
	global_load_dwordx4 v[166:169], v33, s[10:11]
	v_add_u32_e32 v32, s4, v32
	v_add_u32_e32 v33, s5, v33
	global_load_dwordx4 v[170:173], v32, s[8:9]
	global_load_dwordx4 v[174:177], v33, s[10:11]
	v_add_u32_e32 v32, s4, v32
	v_add_u32_e32 v33, s5, v33
	global_load_dwordx4 v[178:181], v32, s[8:9]
	global_load_dwordx4 v[182:185], v33, s[10:11]
	v_add_u32_e32 v32, s4, v32
	v_add_u32_e32 v33, s5, v33
	global_load_dwordx4 v[186:189], v32, s[8:9]
	global_load_dwordx4 v[190:193], v33, s[10:11]
	v_add_u32_e32 v32, s4, v32
	v_add_u32_e32 v33, s5, v33
	s_waitcnt vmcnt(24)
	v_cvt_pk_bf16_f32 v28, v24, v25
	v_cvt_pk_bf16_f32 v29, v26, v27
	global_store_dwordx2 v34, v[28:29], s[12:13]
	v_add_u32_e32 v34, s43, v34
	v_fmac_f32_e32 v194, v24, v198
	v_fmac_f32_e32 v195, v25, v199
	v_fmac_f32_e32 v196, v26, v200
	v_fmac_f32_e32 v197, v27, v201
	v_cvt_pk_bf16_f32 v30, v194, v195
	v_cvt_pk_bf16_f32 v31, v196, v197
	global_store_dwordx2 v34, v[30:31], s[12:13]
	v_add_u32_e32 v34, s43, v34
	v_fmac_f32_e32 v202, v194, v206
	v_fmac_f32_e32 v203, v195, v207
	v_fmac_f32_e32 v204, v196, v208
	v_fmac_f32_e32 v205, v197, v209
	v_cvt_pk_bf16_f32 v28, v202, v203
	v_cvt_pk_bf16_f32 v29, v204, v205
	global_store_dwordx2 v34, v[28:29], s[12:13]
	v_add_u32_e32 v34, s43, v34
	v_fmac_f32_e32 v212, v202, v216
	v_fmac_f32_e32 v213, v203, v217
	v_fmac_f32_e32 v214, v204, v218
	v_fmac_f32_e32 v215, v205, v219
	v_cvt_pk_bf16_f32 v30, v212, v213
	v_cvt_pk_bf16_f32 v31, v214, v215
	global_store_dwordx2 v34, v[30:31], s[12:13]
	v_add_u32_e32 v34, s43, v34
	v_fmac_f32_e32 v220, v212, v224
	v_fmac_f32_e32 v221, v213, v225
	v_fmac_f32_e32 v222, v214, v226
	v_fmac_f32_e32 v223, v215, v227
	v_cvt_pk_bf16_f32 v28, v220, v221
	v_cvt_pk_bf16_f32 v29, v222, v223
	global_store_dwordx2 v34, v[28:29], s[12:13]
	v_add_u32_e32 v34, s43, v34
	v_fmac_f32_e32 v228, v220, v66
	v_fmac_f32_e32 v229, v221, v67
	v_fmac_f32_e32 v230, v222, v68
	v_fmac_f32_e32 v231, v223, v69
	v_cvt_pk_bf16_f32 v30, v228, v229
	v_cvt_pk_bf16_f32 v31, v230, v231
	global_store_dwordx2 v34, v[30:31], s[12:13]
	v_add_u32_e32 v34, s43, v34
	v_fmac_f32_e32 v70, v228, v74
	v_fmac_f32_e32 v71, v229, v75
	v_fmac_f32_e32 v72, v230, v76
	v_fmac_f32_e32 v73, v231, v77
	v_cvt_pk_bf16_f32 v28, v70, v71
	v_cvt_pk_bf16_f32 v29, v72, v73
	global_store_dwordx2 v34, v[28:29], s[12:13]
	v_add_u32_e32 v34, s43, v34
	v_fmac_f32_e32 v78, v70, v8
	v_fmac_f32_e32 v79, v71, v9
	v_fmac_f32_e32 v80, v72, v10
	v_fmac_f32_e32 v81, v73, v11
	v_cvt_pk_bf16_f32 v30, v78, v79
	v_cvt_pk_bf16_f32 v31, v80, v81
	global_store_dwordx2 v34, v[30:31], s[12:13]
	v_add_u32_e32 v34, s43, v34
	v_fmac_f32_e32 v12, v78, v16
	v_fmac_f32_e32 v13, v79, v17
	v_fmac_f32_e32 v14, v80, v18
	v_fmac_f32_e32 v15, v81, v19
	v_mov_b32_e32 v24, v12
	v_mov_b32_e32 v25, v13
	v_mov_b32_e32 v26, v14
	v_mov_b32_e32 v27, v15
	global_load_dwordx4 v[194:197], v32, s[8:9]
	global_load_dwordx4 v[198:201], v33, s[10:11]
	v_add_u32_e32 v32, s4, v32
	v_add_u32_e32 v33, s5, v33
	global_load_dwordx4 v[202:205], v32, s[8:9]
	global_load_dwordx4 v[206:209], v33, s[10:11]
	v_add_u32_e32 v32, s4, v32
	v_add_u32_e32 v33, s5, v33
	global_load_dwordx4 v[212:215], v32, s[8:9]
	global_load_dwordx4 v[216:219], v33, s[10:11]
	v_add_u32_e32 v32, s4, v32
	v_add_u32_e32 v33, s5, v33
	global_load_dwordx4 v[220:223], v32, s[8:9]
	global_load_dwordx4 v[224:227], v33, s[10:11]
	v_add_u32_e32 v32, s4, v32
	v_add_u32_e32 v33, s5, v33
	global_load_dwordx4 v[228:231], v32, s[8:9]
	global_load_dwordx4 v[66:69], v33, s[10:11]
	v_add_u32_e32 v32, s4, v32
	v_add_u32_e32 v33, s5, v33
	global_load_dwordx4 v[70:73], v32, s[8:9]
	global_load_dwordx4 v[74:77], v33, s[10:11]
	v_add_u32_e32 v32, s4, v32
	v_add_u32_e32 v33, s5, v33
	global_load_dwordx4 v[78:81], v32, s[8:9]
	global_load_dwordx4 v[8:11], v33, s[10:11]
	v_add_u32_e32 v32, s4, v32
	v_add_u32_e32 v33, s5, v33
	global_load_dwordx4 v[12:15], v32, s[8:9]
	global_load_dwordx4 v[16:19], v33, s[10:11]
	v_add_u32_e32 v32, s4, v32
	v_add_u32_e32 v33, s5, v33
	s_waitcnt vmcnt(24)
	v_cvt_pk_bf16_f32 v28, v24, v25
	v_cvt_pk_bf16_f32 v29, v26, v27
	global_store_dwordx2 v34, v[28:29], s[12:13]
	v_add_u32_e32 v34, s43, v34
	v_fmac_f32_e32 v130, v24, v134
	v_fmac_f32_e32 v131, v25, v135
	v_fmac_f32_e32 v132, v26, v136
	v_fmac_f32_e32 v133, v27, v137
	v_cvt_pk_bf16_f32 v30, v130, v131
	v_cvt_pk_bf16_f32 v31, v132, v133
	global_store_dwordx2 v34, v[30:31], s[12:13]
	v_add_u32_e32 v34, s43, v34
	v_fmac_f32_e32 v138, v130, v142
	v_fmac_f32_e32 v139, v131, v143
	v_fmac_f32_e32 v140, v132, v144
	v_fmac_f32_e32 v141, v133, v145
	v_cvt_pk_bf16_f32 v28, v138, v139
	v_cvt_pk_bf16_f32 v29, v140, v141
	global_store_dwordx2 v34, v[28:29], s[12:13]
	v_add_u32_e32 v34, s43, v34
	v_fmac_f32_e32 v146, v138, v150
	v_fmac_f32_e32 v147, v139, v151
	v_fmac_f32_e32 v148, v140, v152
	v_fmac_f32_e32 v149, v141, v153
	v_cvt_pk_bf16_f32 v30, v146, v147
	v_cvt_pk_bf16_f32 v31, v148, v149
	global_store_dwordx2 v34, v[30:31], s[12:13]
	v_add_u32_e32 v34, s43, v34
	v_fmac_f32_e32 v154, v146, v158
	v_fmac_f32_e32 v155, v147, v159
	v_fmac_f32_e32 v156, v148, v160
	v_fmac_f32_e32 v157, v149, v161
	v_cvt_pk_bf16_f32 v28, v154, v155
	v_cvt_pk_bf16_f32 v29, v156, v157
	global_store_dwordx2 v34, v[28:29], s[12:13]
	v_add_u32_e32 v34, s43, v34
	v_fmac_f32_e32 v162, v154, v166
	v_fmac_f32_e32 v163, v155, v167
	v_fmac_f32_e32 v164, v156, v168
	v_fmac_f32_e32 v165, v157, v169
	v_cvt_pk_bf16_f32 v30, v162, v163
	v_cvt_pk_bf16_f32 v31, v164, v165
	global_store_dwordx2 v34, v[30:31], s[12:13]
	v_add_u32_e32 v34, s43, v34
	v_fmac_f32_e32 v170, v162, v174
	v_fmac_f32_e32 v171, v163, v175
	v_fmac_f32_e32 v172, v164, v176
	v_fmac_f32_e32 v173, v165, v177
	v_cvt_pk_bf16_f32 v28, v170, v171
	v_cvt_pk_bf16_f32 v29, v172, v173
	global_store_dwordx2 v34, v[28:29], s[12:13]
	v_add_u32_e32 v34, s43, v34
	v_fmac_f32_e32 v178, v170, v182
	v_fmac_f32_e32 v179, v171, v183
	v_fmac_f32_e32 v180, v172, v184
	v_fmac_f32_e32 v181, v173, v185
	v_cvt_pk_bf16_f32 v30, v178, v179
	v_cvt_pk_bf16_f32 v31, v180, v181
	global_store_dwordx2 v34, v[30:31], s[12:13]
	v_add_u32_e32 v34, s43, v34
	v_fmac_f32_e32 v186, v178, v190
	v_fmac_f32_e32 v187, v179, v191
	v_fmac_f32_e32 v188, v180, v192
	v_fmac_f32_e32 v189, v181, v193
	v_mov_b32_e32 v24, v186
	v_mov_b32_e32 v25, v187
	v_mov_b32_e32 v26, v188
	v_mov_b32_e32 v27, v189
	global_load_dwordx4 v[130:133], v32, s[8:9]
	global_load_dwordx4 v[134:137], v33, s[10:11]
	v_add_u32_e32 v32, s4, v32
	v_add_u32_e32 v33, s5, v33
	global_load_dwordx4 v[138:141], v32, s[8:9]
	global_load_dwordx4 v[142:145], v33, s[10:11]
	v_add_u32_e32 v32, s4, v32
	v_add_u32_e32 v33, s5, v33
	global_load_dwordx4 v[146:149], v32, s[8:9]
	global_load_dwordx4 v[150:153], v33, s[10:11]
	v_add_u32_e32 v32, s4, v32
	v_add_u32_e32 v33, s5, v33
	global_load_dwordx4 v[154:157], v32, s[8:9]
	global_load_dwordx4 v[158:161], v33, s[10:11]
	v_add_u32_e32 v32, s4, v32
	v_add_u32_e32 v33, s5, v33
	global_load_dwordx4 v[162:165], v32, s[8:9]
	global_load_dwordx4 v[166:169], v33, s[10:11]
	v_add_u32_e32 v32, s4, v32
	v_add_u32_e32 v33, s5, v33
	global_load_dwordx4 v[170:173], v32, s[8:9]
	global_load_dwordx4 v[174:177], v33, s[10:11]
	v_add_u32_e32 v32, s4, v32
	v_add_u32_e32 v33, s5, v33
	global_load_dwordx4 v[178:181], v32, s[8:9]
	global_load_dwordx4 v[182:185], v33, s[10:11]
	v_add_u32_e32 v32, s4, v32
	v_add_u32_e32 v33, s5, v33
	global_load_dwordx4 v[186:189], v32, s[8:9]
	global_load_dwordx4 v[190:193], v33, s[10:11]
	v_add_u32_e32 v32, s4, v32
	v_add_u32_e32 v33, s5, v33
	s_waitcnt vmcnt(24)
	v_cvt_pk_bf16_f32 v28, v24, v25
	v_cvt_pk_bf16_f32 v29, v26, v27
	global_store_dwordx2 v34, v[28:29], s[12:13]
	v_add_u32_e32 v34, s43, v34
	v_fmac_f32_e32 v194, v24, v198
	v_fmac_f32_e32 v195, v25, v199
	v_fmac_f32_e32 v196, v26, v200
	v_fmac_f32_e32 v197, v27, v201
	v_cvt_pk_bf16_f32 v30, v194, v195
	v_cvt_pk_bf16_f32 v31, v196, v197
	global_store_dwordx2 v34, v[30:31], s[12:13]
	v_add_u32_e32 v34, s43, v34
	v_fmac_f32_e32 v202, v194, v206
	v_fmac_f32_e32 v203, v195, v207
	v_fmac_f32_e32 v204, v196, v208
	v_fmac_f32_e32 v205, v197, v209
	v_cvt_pk_bf16_f32 v28, v202, v203
	v_cvt_pk_bf16_f32 v29, v204, v205
	global_store_dwordx2 v34, v[28:29], s[12:13]
	v_add_u32_e32 v34, s43, v34
	v_fmac_f32_e32 v212, v202, v216
	v_fmac_f32_e32 v213, v203, v217
	v_fmac_f32_e32 v214, v204, v218
	v_fmac_f32_e32 v215, v205, v219
	v_cvt_pk_bf16_f32 v30, v212, v213
	v_cvt_pk_bf16_f32 v31, v214, v215
	global_store_dwordx2 v34, v[30:31], s[12:13]
	v_add_u32_e32 v34, s43, v34
	v_fmac_f32_e32 v220, v212, v224
	v_fmac_f32_e32 v221, v213, v225
	v_fmac_f32_e32 v222, v214, v226
	v_fmac_f32_e32 v223, v215, v227
	v_cvt_pk_bf16_f32 v28, v220, v221
	v_cvt_pk_bf16_f32 v29, v222, v223
	global_store_dwordx2 v34, v[28:29], s[12:13]
	v_add_u32_e32 v34, s43, v34
	v_fmac_f32_e32 v228, v220, v66
	v_fmac_f32_e32 v229, v221, v67
	v_fmac_f32_e32 v230, v222, v68
	v_fmac_f32_e32 v231, v223, v69
	v_cvt_pk_bf16_f32 v30, v228, v229
	v_cvt_pk_bf16_f32 v31, v230, v231
	global_store_dwordx2 v34, v[30:31], s[12:13]
	v_add_u32_e32 v34, s43, v34
	v_fmac_f32_e32 v70, v228, v74
	v_fmac_f32_e32 v71, v229, v75
	v_fmac_f32_e32 v72, v230, v76
	v_fmac_f32_e32 v73, v231, v77
	v_cvt_pk_bf16_f32 v28, v70, v71
	v_cvt_pk_bf16_f32 v29, v72, v73
	global_store_dwordx2 v34, v[28:29], s[12:13]
	v_add_u32_e32 v34, s43, v34
	v_fmac_f32_e32 v78, v70, v8
	v_fmac_f32_e32 v79, v71, v9
	v_fmac_f32_e32 v80, v72, v10
	v_fmac_f32_e32 v81, v73, v11
	v_cvt_pk_bf16_f32 v30, v78, v79
	v_cvt_pk_bf16_f32 v31, v80, v81
	global_store_dwordx2 v34, v[30:31], s[12:13]
	v_add_u32_e32 v34, s43, v34
	v_fmac_f32_e32 v12, v78, v16
	v_fmac_f32_e32 v13, v79, v17
	v_fmac_f32_e32 v14, v80, v18
	v_fmac_f32_e32 v15, v81, v19
	v_mov_b32_e32 v24, v12
	v_mov_b32_e32 v25, v13
	v_mov_b32_e32 v26, v14
	v_mov_b32_e32 v27, v15
	global_load_dwordx4 v[194:197], v32, s[8:9]
	global_load_dwordx4 v[198:201], v33, s[10:11]
	v_add_u32_e32 v32, s4, v32
	v_add_u32_e32 v33, s5, v33
	global_load_dwordx4 v[202:205], v32, s[8:9]
	global_load_dwordx4 v[206:209], v33, s[10:11]
	v_add_u32_e32 v32, s4, v32
	v_add_u32_e32 v33, s5, v33
	global_load_dwordx4 v[212:215], v32, s[8:9]
	global_load_dwordx4 v[216:219], v33, s[10:11]
	v_add_u32_e32 v32, s4, v32
	v_add_u32_e32 v33, s5, v33
	global_load_dwordx4 v[220:223], v32, s[8:9]
	global_load_dwordx4 v[224:227], v33, s[10:11]
	v_add_u32_e32 v32, s4, v32
	v_add_u32_e32 v33, s5, v33
	global_load_dwordx4 v[228:231], v32, s[8:9]
	global_load_dwordx4 v[66:69], v33, s[10:11]
	v_add_u32_e32 v32, s4, v32
	v_add_u32_e32 v33, s5, v33
	global_load_dwordx4 v[70:73], v32, s[8:9]
	global_load_dwordx4 v[74:77], v33, s[10:11]
	v_add_u32_e32 v32, s4, v32
	v_add_u32_e32 v33, s5, v33
	global_load_dwordx4 v[78:81], v32, s[8:9]
	global_load_dwordx4 v[8:11], v33, s[10:11]
	v_add_u32_e32 v32, s4, v32
	v_add_u32_e32 v33, s5, v33
	global_load_dwordx4 v[12:15], v32, s[8:9]
	global_load_dwordx4 v[16:19], v33, s[10:11]
	v_add_u32_e32 v32, s4, v32
	v_add_u32_e32 v33, s5, v33
	s_waitcnt vmcnt(24)
	v_cvt_pk_bf16_f32 v28, v24, v25
	v_cvt_pk_bf16_f32 v29, v26, v27
	global_store_dwordx2 v34, v[28:29], s[12:13]
	v_add_u32_e32 v34, s43, v34
	v_fmac_f32_e32 v130, v24, v134
	v_fmac_f32_e32 v131, v25, v135
	v_fmac_f32_e32 v132, v26, v136
	v_fmac_f32_e32 v133, v27, v137
	v_cvt_pk_bf16_f32 v30, v130, v131
	v_cvt_pk_bf16_f32 v31, v132, v133
	global_store_dwordx2 v34, v[30:31], s[12:13]
	v_add_u32_e32 v34, s43, v34
	v_fmac_f32_e32 v138, v130, v142
	v_fmac_f32_e32 v139, v131, v143
	v_fmac_f32_e32 v140, v132, v144
	v_fmac_f32_e32 v141, v133, v145
	v_cvt_pk_bf16_f32 v28, v138, v139
	v_cvt_pk_bf16_f32 v29, v140, v141
	global_store_dwordx2 v34, v[28:29], s[12:13]
	v_add_u32_e32 v34, s43, v34
	v_fmac_f32_e32 v146, v138, v150
	v_fmac_f32_e32 v147, v139, v151
	v_fmac_f32_e32 v148, v140, v152
	v_fmac_f32_e32 v149, v141, v153
	v_cvt_pk_bf16_f32 v30, v146, v147
	v_cvt_pk_bf16_f32 v31, v148, v149
	global_store_dwordx2 v34, v[30:31], s[12:13]
	v_add_u32_e32 v34, s43, v34
	v_fmac_f32_e32 v154, v146, v158
	v_fmac_f32_e32 v155, v147, v159
	v_fmac_f32_e32 v156, v148, v160
	v_fmac_f32_e32 v157, v149, v161
	v_cvt_pk_bf16_f32 v28, v154, v155
	v_cvt_pk_bf16_f32 v29, v156, v157
	global_store_dwordx2 v34, v[28:29], s[12:13]
	v_add_u32_e32 v34, s43, v34
	v_fmac_f32_e32 v162, v154, v166
	v_fmac_f32_e32 v163, v155, v167
	v_fmac_f32_e32 v164, v156, v168
	v_fmac_f32_e32 v165, v157, v169
	v_cvt_pk_bf16_f32 v30, v162, v163
	v_cvt_pk_bf16_f32 v31, v164, v165
	global_store_dwordx2 v34, v[30:31], s[12:13]
	v_add_u32_e32 v34, s43, v34
	v_fmac_f32_e32 v170, v162, v174
	v_fmac_f32_e32 v171, v163, v175
	v_fmac_f32_e32 v172, v164, v176
	v_fmac_f32_e32 v173, v165, v177
	v_cvt_pk_bf16_f32 v28, v170, v171
	v_cvt_pk_bf16_f32 v29, v172, v173
	global_store_dwordx2 v34, v[28:29], s[12:13]
	v_add_u32_e32 v34, s43, v34
	v_fmac_f32_e32 v178, v170, v182
	v_fmac_f32_e32 v179, v171, v183
	v_fmac_f32_e32 v180, v172, v184
	v_fmac_f32_e32 v181, v173, v185
	v_cvt_pk_bf16_f32 v30, v178, v179
	v_cvt_pk_bf16_f32 v31, v180, v181
	global_store_dwordx2 v34, v[30:31], s[12:13]
	v_add_u32_e32 v34, s43, v34
	v_fmac_f32_e32 v186, v178, v190
	v_fmac_f32_e32 v187, v179, v191
	v_fmac_f32_e32 v188, v180, v192
	v_fmac_f32_e32 v189, v181, v193
	v_mov_b32_e32 v24, v186
	v_mov_b32_e32 v25, v187
	v_mov_b32_e32 v26, v188
	v_mov_b32_e32 v27, v189
	s_waitcnt vmcnt(8)
	v_cvt_pk_bf16_f32 v28, v24, v25
	v_cvt_pk_bf16_f32 v29, v26, v27
	global_store_dwordx2 v34, v[28:29], s[12:13]
	v_add_u32_e32 v34, s43, v34
	v_fmac_f32_e32 v194, v24, v198
	v_fmac_f32_e32 v195, v25, v199
	v_fmac_f32_e32 v196, v26, v200
	v_fmac_f32_e32 v197, v27, v201
	v_cvt_pk_bf16_f32 v30, v194, v195
	v_cvt_pk_bf16_f32 v31, v196, v197
	global_store_dwordx2 v34, v[30:31], s[12:13]
	v_add_u32_e32 v34, s43, v34
	v_fmac_f32_e32 v202, v194, v206
	v_fmac_f32_e32 v203, v195, v207
	v_fmac_f32_e32 v204, v196, v208
	v_fmac_f32_e32 v205, v197, v209
	v_cvt_pk_bf16_f32 v28, v202, v203
	v_cvt_pk_bf16_f32 v29, v204, v205
	global_store_dwordx2 v34, v[28:29], s[12:13]
	v_add_u32_e32 v34, s43, v34
	v_fmac_f32_e32 v212, v202, v216
	v_fmac_f32_e32 v213, v203, v217
	v_fmac_f32_e32 v214, v204, v218
	v_fmac_f32_e32 v215, v205, v219
	v_cvt_pk_bf16_f32 v30, v212, v213
	v_cvt_pk_bf16_f32 v31, v214, v215
	global_store_dwordx2 v34, v[30:31], s[12:13]
	v_add_u32_e32 v34, s43, v34
	v_fmac_f32_e32 v220, v212, v224
	v_fmac_f32_e32 v221, v213, v225
	v_fmac_f32_e32 v222, v214, v226
	v_fmac_f32_e32 v223, v215, v227
	v_cvt_pk_bf16_f32 v28, v220, v221
	v_cvt_pk_bf16_f32 v29, v222, v223
	global_store_dwordx2 v34, v[28:29], s[12:13]
	v_add_u32_e32 v34, s43, v34
	v_fmac_f32_e32 v228, v220, v66
	v_fmac_f32_e32 v229, v221, v67
	v_fmac_f32_e32 v230, v222, v68
	v_fmac_f32_e32 v231, v223, v69
	v_cvt_pk_bf16_f32 v30, v228, v229
	v_cvt_pk_bf16_f32 v31, v230, v231
	global_store_dwordx2 v34, v[30:31], s[12:13]
	v_add_u32_e32 v34, s43, v34
	v_fmac_f32_e32 v70, v228, v74
	v_fmac_f32_e32 v71, v229, v75
	v_fmac_f32_e32 v72, v230, v76
	v_fmac_f32_e32 v73, v231, v77
	v_cvt_pk_bf16_f32 v28, v70, v71
	v_cvt_pk_bf16_f32 v29, v72, v73
	global_store_dwordx2 v34, v[28:29], s[12:13]
	v_add_u32_e32 v34, s43, v34
	v_fmac_f32_e32 v78, v70, v8
	v_fmac_f32_e32 v79, v71, v9
	v_fmac_f32_e32 v80, v72, v10
	v_fmac_f32_e32 v81, v73, v11
	v_cvt_pk_bf16_f32 v30, v78, v79
	v_cvt_pk_bf16_f32 v31, v80, v81
	global_store_dwordx2 v34, v[30:31], s[12:13]
	v_add_u32_e32 v34, s43, v34
	v_fmac_f32_e32 v12, v78, v16
	v_fmac_f32_e32 v13, v79, v17
	v_fmac_f32_e32 v14, v80, v18
	v_fmac_f32_e32 v15, v81, v19
	v_mov_b32_e32 v24, v12
	v_mov_b32_e32 v25, v13
	v_mov_b32_e32 v26, v14
	v_mov_b32_e32 v27, v15
	s_movk_i32 vcc_hi, 0xfd00
	s_mov_b32 vcc_lo, 0x2aaaaaab
